# scan waves: per-step lgkm wait moved into the DPP wait-state filler slot of the previous step (one issue slot less per step)
# baseline (speedup 1.0000x reference)
.LBB0_650:
	s_andn2_saveexec_b64 s[46:47], s[46:47]
	s_cbranch_execz .LBB0_652
	v_add_u32_e32 v136, 0xa000, v95
	ds_read_b128 v[28:31], v92 offset:256
	ds_read_b128 v[102:105], v92 offset:768
	ds_read_b128 v[24:27], v92 offset:0
	ds_read_b128 v[98:101], v92 offset:512
	ds_read_b128 v[106:109], v92 offset:1024
	ds_read2_b32 v[130:131], v136 offset0:0 offset1:16
	ds_read_b128 v[114:117], v92 offset:1536
	ds_read_b128 v[122:125], v92 offset:2048
	ds_read_b128 v[110:113], v92 offset:1280
	ds_read_b128 v[118:121], v92 offset:1792
	ds_read_b128 v[126:129], v92 offset:2304
	s_waitcnt lgkmcnt(5)
	v_pk_mul_f32 v[36:37], v[90:91], v[28:29]
	v_pk_fma_f32 v[36:37], v[88:89], v[30:31], v[36:37]
	v_add_f32_e32 v38, v36, v37
	v_pk_mul_f32 v[40:41], v[102:103], v[130:131] op_sel_hi:[1,0]
	v_pk_mul_f32 v[42:43], v[104:105], v[130:131] op_sel_hi:[1,0]
	v_add_f32_dpp v38, v38, v38 quad_perm:[1,0,3,2] row_mask:0xf bank_mask:0xf bound_ctrl:1
	v_pk_fma_f32 v[40:41], v[90:91], v[24:25], v[40:41]
	v_pk_fma_f32 v[42:43], v[88:89], v[26:27], v[42:43]
	v_add_f32_dpp v38, v38, v38 quad_perm:[2,3,0,1] row_mask:0xf bank_mask:0xf bound_ctrl:1
	s_nop 1
	v_add_f32_dpp v38, v38, v38 row_half_mirror row_mask:0xf bank_mask:0xf bound_ctrl:1
	s_waitcnt lgkmcnt(0)
	s_nop 0
	v_add_f32_dpp v38, v38, v38 row_mirror row_mask:0xf bank_mask:0xf bound_ctrl:1
	v_pk_fma_f32 v[90:91], v[98:99], v[38:39], v[40:41] op_sel_hi:[1,0,1]
	v_pk_fma_f32 v[88:89], v[100:101], v[38:39], v[42:43] op_sel_hi:[1,0,1]
	ds_read_b128 v[28:31], v92 offset:2816
	ds_read_b128 v[102:105], v92 offset:3328
	ds_read_b128 v[24:27], v92 offset:2560
	ds_read_b128 v[98:101], v92 offset:3072
	ds_read_b128 v[50:53], v92 offset:3584
	ds_read2_b32 v[132:133], v136 offset0:32 offset1:48
	v_pk_mul_f32 v[36:37], v[90:91], v[114:115]
	v_pk_fma_f32 v[36:37], v[88:89], v[116:117], v[36:37]
	v_add_f32_e32 v38, v36, v37
	v_pk_mul_f32 v[40:41], v[122:123], v[130:131] op_sel:[0,1] op_sel_hi:[1,1]
	v_pk_mul_f32 v[42:43], v[124:125], v[130:131] op_sel:[0,1] op_sel_hi:[1,1]
	v_add_f32_dpp v38, v38, v38 quad_perm:[1,0,3,2] row_mask:0xf bank_mask:0xf bound_ctrl:1
	v_pk_fma_f32 v[40:41], v[90:91], v[110:111], v[40:41]
	v_pk_fma_f32 v[42:43], v[88:89], v[112:113], v[42:43]
	v_add_f32_dpp v38, v38, v38 quad_perm:[2,3,0,1] row_mask:0xf bank_mask:0xf bound_ctrl:1
	v_pk_mul_f32 v[44:45], v[90:91], v[106:107]
	v_pk_fma_f32 v[44:45], v[88:89], v[108:109], v[44:45]
	v_add_f32_dpp v38, v38, v38 row_half_mirror row_mask:0xf bank_mask:0xf bound_ctrl:1
	v_add_f32_e32 v46, v44, v45
	s_waitcnt lgkmcnt(0)
	v_add_f32_dpp v38, v38, v38 row_mirror row_mask:0xf bank_mask:0xf bound_ctrl:1
	v_pk_fma_f32 v[90:91], v[118:119], v[38:39], v[40:41] op_sel_hi:[1,0,1]
	v_pk_fma_f32 v[88:89], v[120:121], v[38:39], v[42:43] op_sel_hi:[1,0,1]
	ds_read_b128 v[114:117], v92 offset:4096
	ds_read_b128 v[122:125], v92 offset:4608
	ds_read_b128 v[110:113], v92 offset:3840
	ds_read_b128 v[118:121], v92 offset:4352
	ds_read_b128 v[54:57], v92 offset:4864
	v_pk_mul_f32 v[36:37], v[90:91], v[28:29]
	v_pk_fma_f32 v[36:37], v[88:89], v[30:31], v[36:37]
	v_add_f32_e32 v38, v36, v37
	v_pk_mul_f32 v[40:41], v[102:103], v[132:133] op_sel_hi:[1,0]
	v_pk_mul_f32 v[42:43], v[104:105], v[132:133] op_sel_hi:[1,0]
	v_add_f32_dpp v38, v38, v38 quad_perm:[1,0,3,2] row_mask:0xf bank_mask:0xf bound_ctrl:1
	v_pk_fma_f32 v[40:41], v[90:91], v[24:25], v[40:41]
	v_pk_fma_f32 v[42:43], v[88:89], v[26:27], v[42:43]
	v_add_f32_dpp v38, v38, v38 quad_perm:[2,3,0,1] row_mask:0xf bank_mask:0xf bound_ctrl:1
	v_pk_mul_f32 v[44:45], v[90:91], v[126:127]
	v_pk_fma_f32 v[44:45], v[88:89], v[128:129], v[44:45]
	v_add_f32_dpp v38, v38, v38 row_half_mirror row_mask:0xf bank_mask:0xf bound_ctrl:1
	v_add_f32_e32 v47, v44, v45
	s_waitcnt lgkmcnt(0)
	v_add_f32_dpp v38, v38, v38 row_mirror row_mask:0xf bank_mask:0xf bound_ctrl:1
	v_pk_fma_f32 v[90:91], v[98:99], v[38:39], v[40:41] op_sel_hi:[1,0,1]
	v_pk_fma_f32 v[88:89], v[100:101], v[38:39], v[42:43] op_sel_hi:[1,0,1]
	ds_read_b128 v[28:31], v92 offset:5376
	ds_read_b128 v[102:105], v92 offset:5888
	ds_read_b128 v[24:27], v92 offset:5120
	ds_read_b128 v[98:101], v92 offset:5632
	ds_read_b128 v[106:109], v92 offset:6144
	ds_read2_b32 v[130:131], v136 offset0:64 offset1:80
	ds_write2st64_b32 v96, v46, v47 offset0:168 offset1:172
	v_pk_mul_f32 v[36:37], v[90:91], v[114:115]
	v_pk_fma_f32 v[36:37], v[88:89], v[116:117], v[36:37]
	v_add_f32_e32 v38, v36, v37
	v_pk_mul_f32 v[40:41], v[122:123], v[132:133] op_sel:[0,1] op_sel_hi:[1,1]
	v_pk_mul_f32 v[42:43], v[124:125], v[132:133] op_sel:[0,1] op_sel_hi:[1,1]
	v_add_f32_dpp v38, v38, v38 quad_perm:[1,0,3,2] row_mask:0xf bank_mask:0xf bound_ctrl:1
	v_pk_fma_f32 v[40:41], v[90:91], v[110:111], v[40:41]
	v_pk_fma_f32 v[42:43], v[88:89], v[112:113], v[42:43]
	v_add_f32_dpp v38, v38, v38 quad_perm:[2,3,0,1] row_mask:0xf bank_mask:0xf bound_ctrl:1
	v_pk_mul_f32 v[44:45], v[90:91], v[50:51]
	v_pk_fma_f32 v[44:45], v[88:89], v[52:53], v[44:45]
	v_add_f32_dpp v38, v38, v38 row_half_mirror row_mask:0xf bank_mask:0xf bound_ctrl:1
	v_add_f32_e32 v48, v44, v45
	s_waitcnt lgkmcnt(0)
	v_add_f32_dpp v38, v38, v38 row_mirror row_mask:0xf bank_mask:0xf bound_ctrl:1
	v_pk_fma_f32 v[90:91], v[118:119], v[38:39], v[40:41] op_sel_hi:[1,0,1]
	v_pk_fma_f32 v[88:89], v[120:121], v[38:39], v[42:43] op_sel_hi:[1,0,1]
	ds_read_b128 v[114:117], v92 offset:6656
	ds_read_b128 v[122:125], v92 offset:7168
	ds_read_b128 v[110:113], v92 offset:6400
	ds_read_b128 v[118:121], v92 offset:6912
	ds_read_b128 v[126:129], v92 offset:7424
	v_pk_mul_f32 v[36:37], v[90:91], v[28:29]
	v_pk_fma_f32 v[36:37], v[88:89], v[30:31], v[36:37]
	v_add_f32_e32 v38, v36, v37
	v_pk_mul_f32 v[40:41], v[102:103], v[130:131] op_sel_hi:[1,0]
	v_pk_mul_f32 v[42:43], v[104:105], v[130:131] op_sel_hi:[1,0]
	v_add_f32_dpp v38, v38, v38 quad_perm:[1,0,3,2] row_mask:0xf bank_mask:0xf bound_ctrl:1
	v_pk_fma_f32 v[40:41], v[90:91], v[24:25], v[40:41]
	v_pk_fma_f32 v[42:43], v[88:89], v[26:27], v[42:43]
	v_add_f32_dpp v38, v38, v38 quad_perm:[2,3,0,1] row_mask:0xf bank_mask:0xf bound_ctrl:1
	v_pk_mul_f32 v[44:45], v[90:91], v[54:55]
	v_pk_fma_f32 v[44:45], v[88:89], v[56:57], v[44:45]
	v_add_f32_dpp v38, v38, v38 row_half_mirror row_mask:0xf bank_mask:0xf bound_ctrl:1
	v_add_f32_e32 v49, v44, v45
	s_waitcnt lgkmcnt(0)
	v_add_f32_dpp v38, v38, v38 row_mirror row_mask:0xf bank_mask:0xf bound_ctrl:1
	v_pk_fma_f32 v[90:91], v[98:99], v[38:39], v[40:41] op_sel_hi:[1,0,1]
	v_pk_fma_f32 v[88:89], v[100:101], v[38:39], v[42:43] op_sel_hi:[1,0,1]
	ds_read_b128 v[28:31], v92 offset:7936
	ds_read_b128 v[102:105], v92 offset:8448
	ds_read_b128 v[24:27], v92 offset:7680
	ds_read_b128 v[98:101], v92 offset:8192
	ds_read_b128 v[50:53], v92 offset:8704
	ds_read2_b32 v[132:133], v136 offset0:96 offset1:112
	ds_write2st64_b32 v96, v48, v49 offset0:176 offset1:180
	v_pk_mul_f32 v[36:37], v[90:91], v[114:115]
	v_pk_fma_f32 v[36:37], v[88:89], v[116:117], v[36:37]
	v_add_f32_e32 v38, v36, v37
	v_pk_mul_f32 v[40:41], v[122:123], v[130:131] op_sel:[0,1] op_sel_hi:[1,1]
	v_pk_mul_f32 v[42:43], v[124:125], v[130:131] op_sel:[0,1] op_sel_hi:[1,1]
	v_add_f32_dpp v38, v38, v38 quad_perm:[1,0,3,2] row_mask:0xf bank_mask:0xf bound_ctrl:1
	v_pk_fma_f32 v[40:41], v[90:91], v[110:111], v[40:41]
	v_pk_fma_f32 v[42:43], v[88:89], v[112:113], v[42:43]
	v_add_f32_dpp v38, v38, v38 quad_perm:[2,3,0,1] row_mask:0xf bank_mask:0xf bound_ctrl:1
	v_pk_mul_f32 v[44:45], v[90:91], v[106:107]
	v_pk_fma_f32 v[44:45], v[88:89], v[108:109], v[44:45]
	v_add_f32_dpp v38, v38, v38 row_half_mirror row_mask:0xf bank_mask:0xf bound_ctrl:1
	v_add_f32_e32 v46, v44, v45
	s_waitcnt lgkmcnt(0)
	v_add_f32_dpp v38, v38, v38 row_mirror row_mask:0xf bank_mask:0xf bound_ctrl:1
	v_pk_fma_f32 v[90:91], v[118:119], v[38:39], v[40:41] op_sel_hi:[1,0,1]
	v_pk_fma_f32 v[88:89], v[120:121], v[38:39], v[42:43] op_sel_hi:[1,0,1]
	ds_read_b128 v[114:117], v92 offset:9216
	ds_read_b128 v[122:125], v92 offset:9728
	ds_read_b128 v[110:113], v92 offset:8960
	ds_read_b128 v[118:121], v92 offset:9472
	ds_read_b128 v[54:57], v92 offset:9984
	v_pk_mul_f32 v[36:37], v[90:91], v[28:29]
	v_pk_fma_f32 v[36:37], v[88:89], v[30:31], v[36:37]
	v_add_f32_e32 v38, v36, v37
	v_pk_mul_f32 v[40:41], v[102:103], v[132:133] op_sel_hi:[1,0]
	v_pk_mul_f32 v[42:43], v[104:105], v[132:133] op_sel_hi:[1,0]
	v_add_f32_dpp v38, v38, v38 quad_perm:[1,0,3,2] row_mask:0xf bank_mask:0xf bound_ctrl:1
	v_pk_fma_f32 v[40:41], v[90:91], v[24:25], v[40:41]
	v_pk_fma_f32 v[42:43], v[88:89], v[26:27], v[42:43]
	v_add_f32_dpp v38, v38, v38 quad_perm:[2,3,0,1] row_mask:0xf bank_mask:0xf bound_ctrl:1
	v_pk_mul_f32 v[44:45], v[90:91], v[126:127]
	v_pk_fma_f32 v[44:45], v[88:89], v[128:129], v[44:45]
	v_add_f32_dpp v38, v38, v38 row_half_mirror row_mask:0xf bank_mask:0xf bound_ctrl:1
	v_add_f32_e32 v47, v44, v45
	s_waitcnt lgkmcnt(0)
	v_add_f32_dpp v38, v38, v38 row_mirror row_mask:0xf bank_mask:0xf bound_ctrl:1
	v_pk_fma_f32 v[90:91], v[98:99], v[38:39], v[40:41] op_sel_hi:[1,0,1]
	v_pk_fma_f32 v[88:89], v[100:101], v[38:39], v[42:43] op_sel_hi:[1,0,1]
	ds_read_b128 v[28:31], v92 offset:10496
	ds_read_b128 v[102:105], v92 offset:11008
	ds_read_b128 v[24:27], v92 offset:10240
	ds_read_b128 v[98:101], v92 offset:10752
	ds_read_b128 v[106:109], v92 offset:11264
	ds_read2_b32 v[130:131], v136 offset0:128 offset1:144
	ds_write2st64_b32 v96, v46, v47 offset0:184 offset1:188
	v_pk_mul_f32 v[36:37], v[90:91], v[114:115]
	v_pk_fma_f32 v[36:37], v[88:89], v[116:117], v[36:37]
	v_add_f32_e32 v38, v36, v37
	v_pk_mul_f32 v[40:41], v[122:123], v[132:133] op_sel:[0,1] op_sel_hi:[1,1]
	v_pk_mul_f32 v[42:43], v[124:125], v[132:133] op_sel:[0,1] op_sel_hi:[1,1]
	v_add_f32_dpp v38, v38, v38 quad_perm:[1,0,3,2] row_mask:0xf bank_mask:0xf bound_ctrl:1
	v_pk_fma_f32 v[40:41], v[90:91], v[110:111], v[40:41]
	v_pk_fma_f32 v[42:43], v[88:89], v[112:113], v[42:43]
	v_add_f32_dpp v38, v38, v38 quad_perm:[2,3,0,1] row_mask:0xf bank_mask:0xf bound_ctrl:1
	v_pk_mul_f32 v[44:45], v[90:91], v[50:51]
	v_pk_fma_f32 v[44:45], v[88:89], v[52:53], v[44:45]
	v_add_f32_dpp v38, v38, v38 row_half_mirror row_mask:0xf bank_mask:0xf bound_ctrl:1
	v_add_f32_e32 v48, v44, v45
	s_waitcnt lgkmcnt(0)
	v_add_f32_dpp v38, v38, v38 row_mirror row_mask:0xf bank_mask:0xf bound_ctrl:1
	v_pk_fma_f32 v[90:91], v[118:119], v[38:39], v[40:41] op_sel_hi:[1,0,1]
	v_pk_fma_f32 v[88:89], v[120:121], v[38:39], v[42:43] op_sel_hi:[1,0,1]
	ds_read_b128 v[114:117], v92 offset:11776
	ds_read_b128 v[122:125], v92 offset:12288
	ds_read_b128 v[110:113], v92 offset:11520
	ds_read_b128 v[118:121], v92 offset:12032
	ds_read_b128 v[126:129], v92 offset:12544
	v_pk_mul_f32 v[36:37], v[90:91], v[28:29]
	v_pk_fma_f32 v[36:37], v[88:89], v[30:31], v[36:37]
	v_add_f32_e32 v38, v36, v37
	v_pk_mul_f32 v[40:41], v[102:103], v[130:131] op_sel_hi:[1,0]
	v_pk_mul_f32 v[42:43], v[104:105], v[130:131] op_sel_hi:[1,0]
	v_add_f32_dpp v38, v38, v38 quad_perm:[1,0,3,2] row_mask:0xf bank_mask:0xf bound_ctrl:1
	v_pk_fma_f32 v[40:41], v[90:91], v[24:25], v[40:41]
	v_pk_fma_f32 v[42:43], v[88:89], v[26:27], v[42:43]
	v_add_f32_dpp v38, v38, v38 quad_perm:[2,3,0,1] row_mask:0xf bank_mask:0xf bound_ctrl:1
	v_pk_mul_f32 v[44:45], v[90:91], v[54:55]
	v_pk_fma_f32 v[44:45], v[88:89], v[56:57], v[44:45]
	v_add_f32_dpp v38, v38, v38 row_half_mirror row_mask:0xf bank_mask:0xf bound_ctrl:1
	v_add_f32_e32 v49, v44, v45
	s_waitcnt lgkmcnt(0)
	v_add_f32_dpp v38, v38, v38 row_mirror row_mask:0xf bank_mask:0xf bound_ctrl:1
	v_pk_fma_f32 v[90:91], v[98:99], v[38:39], v[40:41] op_sel_hi:[1,0,1]
	v_pk_fma_f32 v[88:89], v[100:101], v[38:39], v[42:43] op_sel_hi:[1,0,1]
	ds_read_b128 v[28:31], v92 offset:13056
	ds_read_b128 v[102:105], v92 offset:13568
	ds_read_b128 v[24:27], v92 offset:12800
	ds_read_b128 v[98:101], v92 offset:13312
	ds_read_b128 v[50:53], v92 offset:13824
	ds_read2_b32 v[132:133], v136 offset0:160 offset1:176
	ds_write2st64_b32 v96, v48, v49 offset0:192 offset1:196
	v_pk_mul_f32 v[36:37], v[90:91], v[114:115]
	v_pk_fma_f32 v[36:37], v[88:89], v[116:117], v[36:37]
	v_add_f32_e32 v38, v36, v37
	v_pk_mul_f32 v[40:41], v[122:123], v[130:131] op_sel:[0,1] op_sel_hi:[1,1]
	v_pk_mul_f32 v[42:43], v[124:125], v[130:131] op_sel:[0,1] op_sel_hi:[1,1]
	v_add_f32_dpp v38, v38, v38 quad_perm:[1,0,3,2] row_mask:0xf bank_mask:0xf bound_ctrl:1
	v_pk_fma_f32 v[40:41], v[90:91], v[110:111], v[40:41]
	v_pk_fma_f32 v[42:43], v[88:89], v[112:113], v[42:43]
	v_add_f32_dpp v38, v38, v38 quad_perm:[2,3,0,1] row_mask:0xf bank_mask:0xf bound_ctrl:1
	v_pk_mul_f32 v[44:45], v[90:91], v[106:107]
	v_pk_fma_f32 v[44:45], v[88:89], v[108:109], v[44:45]
	v_add_f32_dpp v38, v38, v38 row_half_mirror row_mask:0xf bank_mask:0xf bound_ctrl:1
	v_add_f32_e32 v46, v44, v45
	s_waitcnt lgkmcnt(0)
	v_add_f32_dpp v38, v38, v38 row_mirror row_mask:0xf bank_mask:0xf bound_ctrl:1
	v_pk_fma_f32 v[90:91], v[118:119], v[38:39], v[40:41] op_sel_hi:[1,0,1]
	v_pk_fma_f32 v[88:89], v[120:121], v[38:39], v[42:43] op_sel_hi:[1,0,1]
	ds_read_b128 v[114:117], v92 offset:14336
	ds_read_b128 v[122:125], v92 offset:14848
	ds_read_b128 v[110:113], v92 offset:14080
	ds_read_b128 v[118:121], v92 offset:14592
	ds_read_b128 v[54:57], v92 offset:15104
	v_pk_mul_f32 v[36:37], v[90:91], v[28:29]
	v_pk_fma_f32 v[36:37], v[88:89], v[30:31], v[36:37]
	v_add_f32_e32 v38, v36, v37
	v_pk_mul_f32 v[40:41], v[102:103], v[132:133] op_sel_hi:[1,0]
	v_pk_mul_f32 v[42:43], v[104:105], v[132:133] op_sel_hi:[1,0]
	v_add_f32_dpp v38, v38, v38 quad_perm:[1,0,3,2] row_mask:0xf bank_mask:0xf bound_ctrl:1
	v_pk_fma_f32 v[40:41], v[90:91], v[24:25], v[40:41]
	v_pk_fma_f32 v[42:43], v[88:89], v[26:27], v[42:43]
	v_add_f32_dpp v38, v38, v38 quad_perm:[2,3,0,1] row_mask:0xf bank_mask:0xf bound_ctrl:1
	v_pk_mul_f32 v[44:45], v[90:91], v[126:127]
	v_pk_fma_f32 v[44:45], v[88:89], v[128:129], v[44:45]
	v_add_f32_dpp v38, v38, v38 row_half_mirror row_mask:0xf bank_mask:0xf bound_ctrl:1
	v_add_f32_e32 v47, v44, v45
	s_waitcnt lgkmcnt(0)
	v_add_f32_dpp v38, v38, v38 row_mirror row_mask:0xf bank_mask:0xf bound_ctrl:1
	v_pk_fma_f32 v[90:91], v[98:99], v[38:39], v[40:41] op_sel_hi:[1,0,1]
	v_pk_fma_f32 v[88:89], v[100:101], v[38:39], v[42:43] op_sel_hi:[1,0,1]
	ds_read_b128 v[28:31], v92 offset:15616
	ds_read_b128 v[102:105], v92 offset:16128
	ds_read_b128 v[24:27], v92 offset:15360
	ds_read_b128 v[98:101], v92 offset:15872
	ds_read_b128 v[106:109], v92 offset:16384
	ds_read2_b32 v[130:131], v136 offset0:192 offset1:208
	ds_write2st64_b32 v96, v46, v47 offset0:200 offset1:204
	v_pk_mul_f32 v[36:37], v[90:91], v[114:115]
	v_pk_fma_f32 v[36:37], v[88:89], v[116:117], v[36:37]
	v_add_f32_e32 v38, v36, v37
	v_pk_mul_f32 v[40:41], v[122:123], v[132:133] op_sel:[0,1] op_sel_hi:[1,1]
	v_pk_mul_f32 v[42:43], v[124:125], v[132:133] op_sel:[0,1] op_sel_hi:[1,1]
	v_add_f32_dpp v38, v38, v38 quad_perm:[1,0,3,2] row_mask:0xf bank_mask:0xf bound_ctrl:1
	v_pk_fma_f32 v[40:41], v[90:91], v[110:111], v[40:41]
	v_pk_fma_f32 v[42:43], v[88:89], v[112:113], v[42:43]
	v_add_f32_dpp v38, v38, v38 quad_perm:[2,3,0,1] row_mask:0xf bank_mask:0xf bound_ctrl:1
	v_pk_mul_f32 v[44:45], v[90:91], v[50:51]
	v_pk_fma_f32 v[44:45], v[88:89], v[52:53], v[44:45]
	v_add_f32_dpp v38, v38, v38 row_half_mirror row_mask:0xf bank_mask:0xf bound_ctrl:1
	v_add_f32_e32 v48, v44, v45
	s_waitcnt lgkmcnt(0)
	v_add_f32_dpp v38, v38, v38 row_mirror row_mask:0xf bank_mask:0xf bound_ctrl:1
	v_pk_fma_f32 v[90:91], v[118:119], v[38:39], v[40:41] op_sel_hi:[1,0,1]
	v_pk_fma_f32 v[88:89], v[120:121], v[38:39], v[42:43] op_sel_hi:[1,0,1]
	ds_read_b128 v[114:117], v92 offset:16896
	ds_read_b128 v[122:125], v92 offset:17408
	ds_read_b128 v[110:113], v92 offset:16640
	ds_read_b128 v[118:121], v92 offset:17152
	ds_read_b128 v[126:129], v92 offset:17664
	v_pk_mul_f32 v[36:37], v[90:91], v[28:29]
	v_pk_fma_f32 v[36:37], v[88:89], v[30:31], v[36:37]
	v_add_f32_e32 v38, v36, v37
	v_pk_mul_f32 v[40:41], v[102:103], v[130:131] op_sel_hi:[1,0]
	v_pk_mul_f32 v[42:43], v[104:105], v[130:131] op_sel_hi:[1,0]
	v_add_f32_dpp v38, v38, v38 quad_perm:[1,0,3,2] row_mask:0xf bank_mask:0xf bound_ctrl:1
	v_pk_fma_f32 v[40:41], v[90:91], v[24:25], v[40:41]
	v_pk_fma_f32 v[42:43], v[88:89], v[26:27], v[42:43]
	v_add_f32_dpp v38, v38, v38 quad_perm:[2,3,0,1] row_mask:0xf bank_mask:0xf bound_ctrl:1
	v_pk_mul_f32 v[44:45], v[90:91], v[54:55]
	v_pk_fma_f32 v[44:45], v[88:89], v[56:57], v[44:45]
	v_add_f32_dpp v38, v38, v38 row_half_mirror row_mask:0xf bank_mask:0xf bound_ctrl:1
	v_add_f32_e32 v49, v44, v45
	s_waitcnt lgkmcnt(0)
	v_add_f32_dpp v38, v38, v38 row_mirror row_mask:0xf bank_mask:0xf bound_ctrl:1
	v_pk_fma_f32 v[90:91], v[98:99], v[38:39], v[40:41] op_sel_hi:[1,0,1]
	v_pk_fma_f32 v[88:89], v[100:101], v[38:39], v[42:43] op_sel_hi:[1,0,1]
	ds_read_b128 v[28:31], v92 offset:18176
	ds_read_b128 v[102:105], v92 offset:18688
	ds_read_b128 v[24:27], v92 offset:17920
	ds_read_b128 v[98:101], v92 offset:18432
	ds_read_b128 v[50:53], v92 offset:18944
	ds_read2_b32 v[132:133], v136 offset0:224 offset1:240
	ds_write2st64_b32 v96, v48, v49 offset0:208 offset1:212
	v_pk_mul_f32 v[36:37], v[90:91], v[114:115]
	v_pk_fma_f32 v[36:37], v[88:89], v[116:117], v[36:37]
	v_add_f32_e32 v38, v36, v37
	v_pk_mul_f32 v[40:41], v[122:123], v[130:131] op_sel:[0,1] op_sel_hi:[1,1]
	v_pk_mul_f32 v[42:43], v[124:125], v[130:131] op_sel:[0,1] op_sel_hi:[1,1]
	v_add_f32_dpp v38, v38, v38 quad_perm:[1,0,3,2] row_mask:0xf bank_mask:0xf bound_ctrl:1
	v_pk_fma_f32 v[40:41], v[90:91], v[110:111], v[40:41]
	v_pk_fma_f32 v[42:43], v[88:89], v[112:113], v[42:43]
	v_add_f32_dpp v38, v38, v38 quad_perm:[2,3,0,1] row_mask:0xf bank_mask:0xf bound_ctrl:1
	v_pk_mul_f32 v[44:45], v[90:91], v[106:107]
	v_pk_fma_f32 v[44:45], v[88:89], v[108:109], v[44:45]
	v_add_f32_dpp v38, v38, v38 row_half_mirror row_mask:0xf bank_mask:0xf bound_ctrl:1
	v_add_f32_e32 v46, v44, v45
	s_waitcnt lgkmcnt(0)
	v_add_f32_dpp v38, v38, v38 row_mirror row_mask:0xf bank_mask:0xf bound_ctrl:1
	v_pk_fma_f32 v[90:91], v[118:119], v[38:39], v[40:41] op_sel_hi:[1,0,1]
	v_pk_fma_f32 v[88:89], v[120:121], v[38:39], v[42:43] op_sel_hi:[1,0,1]
	ds_read_b128 v[114:117], v92 offset:19456
	ds_read_b128 v[122:125], v92 offset:19968
	ds_read_b128 v[110:113], v92 offset:19200
	ds_read_b128 v[118:121], v92 offset:19712
	ds_read_b128 v[54:57], v92 offset:20224
	v_pk_mul_f32 v[36:37], v[90:91], v[28:29]
	v_pk_fma_f32 v[36:37], v[88:89], v[30:31], v[36:37]
	v_add_f32_e32 v38, v36, v37
	v_pk_mul_f32 v[40:41], v[102:103], v[132:133] op_sel_hi:[1,0]
	v_pk_mul_f32 v[42:43], v[104:105], v[132:133] op_sel_hi:[1,0]
	v_add_f32_dpp v38, v38, v38 quad_perm:[1,0,3,2] row_mask:0xf bank_mask:0xf bound_ctrl:1
	v_pk_fma_f32 v[40:41], v[90:91], v[24:25], v[40:41]
	v_pk_fma_f32 v[42:43], v[88:89], v[26:27], v[42:43]
	v_add_f32_dpp v38, v38, v38 quad_perm:[2,3,0,1] row_mask:0xf bank_mask:0xf bound_ctrl:1
	v_pk_mul_f32 v[44:45], v[90:91], v[126:127]
	v_pk_fma_f32 v[44:45], v[88:89], v[128:129], v[44:45]
	v_add_f32_dpp v38, v38, v38 row_half_mirror row_mask:0xf bank_mask:0xf bound_ctrl:1
	v_add_f32_e32 v47, v44, v45
	s_waitcnt lgkmcnt(0)
	v_add_f32_dpp v38, v38, v38 row_mirror row_mask:0xf bank_mask:0xf bound_ctrl:1
	v_pk_fma_f32 v[90:91], v[98:99], v[38:39], v[40:41] op_sel_hi:[1,0,1]
	v_pk_fma_f32 v[88:89], v[100:101], v[38:39], v[42:43] op_sel_hi:[1,0,1]
	ds_write2st64_b32 v96, v46, v47 offset0:216 offset1:220
	v_pk_mul_f32 v[36:37], v[90:91], v[114:115]
	v_pk_fma_f32 v[36:37], v[88:89], v[116:117], v[36:37]
	v_add_f32_e32 v38, v36, v37
	v_pk_mul_f32 v[40:41], v[122:123], v[132:133] op_sel:[0,1] op_sel_hi:[1,1]
	v_pk_mul_f32 v[42:43], v[124:125], v[132:133] op_sel:[0,1] op_sel_hi:[1,1]
	v_add_f32_dpp v38, v38, v38 quad_perm:[1,0,3,2] row_mask:0xf bank_mask:0xf bound_ctrl:1
	v_pk_fma_f32 v[40:41], v[90:91], v[110:111], v[40:41]
	v_pk_fma_f32 v[42:43], v[88:89], v[112:113], v[42:43]
	v_add_f32_dpp v38, v38, v38 quad_perm:[2,3,0,1] row_mask:0xf bank_mask:0xf bound_ctrl:1
	v_pk_mul_f32 v[44:45], v[90:91], v[50:51]
	v_pk_fma_f32 v[44:45], v[88:89], v[52:53], v[44:45]
	v_add_f32_dpp v38, v38, v38 row_half_mirror row_mask:0xf bank_mask:0xf bound_ctrl:1
	v_add_f32_e32 v48, v44, v45
	s_nop 0
	v_add_f32_dpp v38, v38, v38 row_mirror row_mask:0xf bank_mask:0xf bound_ctrl:1
	v_pk_fma_f32 v[90:91], v[118:119], v[38:39], v[40:41] op_sel_hi:[1,0,1]
	v_pk_fma_f32 v[88:89], v[120:121], v[38:39], v[42:43] op_sel_hi:[1,0,1]
	v_pk_mul_f32 v[44:45], v[90:91], v[54:55]
	v_pk_fma_f32 v[44:45], v[88:89], v[56:57], v[44:45]
	v_add_f32_e32 v49, v44, v45
	ds_write2st64_b32 v96, v48, v49 offset0:224 offset1:228

.LBB0_660:
	s_andn2_saveexec_b64 s[46:47], s[46:47]
	s_cbranch_execz .LBB0_640
	v_add_u32_e32 v136, 0xa400, v95
	ds_read_b128 v[28:31], v92 offset:20736
	ds_read_b128 v[102:105], v92 offset:21248
	ds_read_b128 v[24:27], v92 offset:20480
	ds_read_b128 v[98:101], v92 offset:20992
	ds_read_b128 v[106:109], v92 offset:21504
	ds_read2_b32 v[130:131], v136 offset0:0 offset1:16
	ds_read_b128 v[114:117], v92 offset:22016
	ds_read_b128 v[122:125], v92 offset:22528
	ds_read_b128 v[110:113], v92 offset:21760
	ds_read_b128 v[118:121], v92 offset:22272
	ds_read_b128 v[126:129], v92 offset:22784
	s_waitcnt lgkmcnt(5)
	v_pk_mul_f32 v[36:37], v[90:91], v[28:29]
	v_pk_fma_f32 v[36:37], v[88:89], v[30:31], v[36:37]
	v_add_f32_e32 v38, v36, v37
	v_pk_mul_f32 v[40:41], v[102:103], v[130:131] op_sel_hi:[1,0]
	v_pk_mul_f32 v[42:43], v[104:105], v[130:131] op_sel_hi:[1,0]
	v_add_f32_dpp v38, v38, v38 quad_perm:[1,0,3,2] row_mask:0xf bank_mask:0xf bound_ctrl:1
	v_pk_fma_f32 v[40:41], v[90:91], v[24:25], v[40:41]
	v_pk_fma_f32 v[42:43], v[88:89], v[26:27], v[42:43]
	v_add_f32_dpp v38, v38, v38 quad_perm:[2,3,0,1] row_mask:0xf bank_mask:0xf bound_ctrl:1
	s_nop 1
	v_add_f32_dpp v38, v38, v38 row_half_mirror row_mask:0xf bank_mask:0xf bound_ctrl:1
	s_waitcnt lgkmcnt(0)
	s_nop 0
	v_add_f32_dpp v38, v38, v38 row_mirror row_mask:0xf bank_mask:0xf bound_ctrl:1
	v_pk_fma_f32 v[90:91], v[98:99], v[38:39], v[40:41] op_sel_hi:[1,0,1]
	v_pk_fma_f32 v[88:89], v[100:101], v[38:39], v[42:43] op_sel_hi:[1,0,1]
	ds_read_b128 v[28:31], v92 offset:23296
	ds_read_b128 v[102:105], v92 offset:23808
	ds_read_b128 v[24:27], v92 offset:23040
	ds_read_b128 v[98:101], v92 offset:23552
	ds_read_b128 v[50:53], v92 offset:24064
	ds_read2_b32 v[132:133], v136 offset0:32 offset1:48
	v_pk_mul_f32 v[36:37], v[90:91], v[114:115]
	v_pk_fma_f32 v[36:37], v[88:89], v[116:117], v[36:37]
	v_add_f32_e32 v38, v36, v37
	v_pk_mul_f32 v[40:41], v[122:123], v[130:131] op_sel:[0,1] op_sel_hi:[1,1]
	v_pk_mul_f32 v[42:43], v[124:125], v[130:131] op_sel:[0,1] op_sel_hi:[1,1]
	v_add_f32_dpp v38, v38, v38 quad_perm:[1,0,3,2] row_mask:0xf bank_mask:0xf bound_ctrl:1
	v_pk_fma_f32 v[40:41], v[90:91], v[110:111], v[40:41]
	v_pk_fma_f32 v[42:43], v[88:89], v[112:113], v[42:43]
	v_add_f32_dpp v38, v38, v38 quad_perm:[2,3,0,1] row_mask:0xf bank_mask:0xf bound_ctrl:1
	v_pk_mul_f32 v[44:45], v[90:91], v[106:107]
	v_pk_fma_f32 v[44:45], v[88:89], v[108:109], v[44:45]
	v_add_f32_dpp v38, v38, v38 row_half_mirror row_mask:0xf bank_mask:0xf bound_ctrl:1
	v_add_f32_e32 v46, v44, v45
	s_waitcnt lgkmcnt(0)
	v_add_f32_dpp v38, v38, v38 row_mirror row_mask:0xf bank_mask:0xf bound_ctrl:1
	v_pk_fma_f32 v[90:91], v[118:119], v[38:39], v[40:41] op_sel_hi:[1,0,1]
	v_pk_fma_f32 v[88:89], v[120:121], v[38:39], v[42:43] op_sel_hi:[1,0,1]
	ds_read_b128 v[114:117], v92 offset:24576
	ds_read_b128 v[122:125], v92 offset:25088
	ds_read_b128 v[110:113], v92 offset:24320
	ds_read_b128 v[118:121], v92 offset:24832
	ds_read_b128 v[54:57], v92 offset:25344
	v_pk_mul_f32 v[36:37], v[90:91], v[28:29]
	v_pk_fma_f32 v[36:37], v[88:89], v[30:31], v[36:37]
	v_add_f32_e32 v38, v36, v37
	v_pk_mul_f32 v[40:41], v[102:103], v[132:133] op_sel_hi:[1,0]
	v_pk_mul_f32 v[42:43], v[104:105], v[132:133] op_sel_hi:[1,0]
	v_add_f32_dpp v38, v38, v38 quad_perm:[1,0,3,2] row_mask:0xf bank_mask:0xf bound_ctrl:1
	v_pk_fma_f32 v[40:41], v[90:91], v[24:25], v[40:41]
	v_pk_fma_f32 v[42:43], v[88:89], v[26:27], v[42:43]
	v_add_f32_dpp v38, v38, v38 quad_perm:[2,3,0,1] row_mask:0xf bank_mask:0xf bound_ctrl:1
	v_pk_mul_f32 v[44:45], v[90:91], v[126:127]
	v_pk_fma_f32 v[44:45], v[88:89], v[128:129], v[44:45]
	v_add_f32_dpp v38, v38, v38 row_half_mirror row_mask:0xf bank_mask:0xf bound_ctrl:1
	v_add_f32_e32 v47, v44, v45
	s_waitcnt lgkmcnt(0)
	v_add_f32_dpp v38, v38, v38 row_mirror row_mask:0xf bank_mask:0xf bound_ctrl:1
	v_pk_fma_f32 v[90:91], v[98:99], v[38:39], v[40:41] op_sel_hi:[1,0,1]
	v_pk_fma_f32 v[88:89], v[100:101], v[38:39], v[42:43] op_sel_hi:[1,0,1]
	ds_read_b128 v[28:31], v92 offset:25856
	ds_read_b128 v[102:105], v92 offset:26368
	ds_read_b128 v[24:27], v92 offset:25600
	ds_read_b128 v[98:101], v92 offset:26112
	ds_read_b128 v[106:109], v92 offset:26624
	ds_read2_b32 v[130:131], v136 offset0:64 offset1:80
	ds_write2st64_b32 v97, v46, v47 offset0:64 offset1:68
	v_pk_mul_f32 v[36:37], v[90:91], v[114:115]
	v_pk_fma_f32 v[36:37], v[88:89], v[116:117], v[36:37]
	v_add_f32_e32 v38, v36, v37
	v_pk_mul_f32 v[40:41], v[122:123], v[132:133] op_sel:[0,1] op_sel_hi:[1,1]
	v_pk_mul_f32 v[42:43], v[124:125], v[132:133] op_sel:[0,1] op_sel_hi:[1,1]
	v_add_f32_dpp v38, v38, v38 quad_perm:[1,0,3,2] row_mask:0xf bank_mask:0xf bound_ctrl:1
	v_pk_fma_f32 v[40:41], v[90:91], v[110:111], v[40:41]
	v_pk_fma_f32 v[42:43], v[88:89], v[112:113], v[42:43]
	v_add_f32_dpp v38, v38, v38 quad_perm:[2,3,0,1] row_mask:0xf bank_mask:0xf bound_ctrl:1
	v_pk_mul_f32 v[44:45], v[90:91], v[50:51]
	v_pk_fma_f32 v[44:45], v[88:89], v[52:53], v[44:45]
	v_add_f32_dpp v38, v38, v38 row_half_mirror row_mask:0xf bank_mask:0xf bound_ctrl:1
	v_add_f32_e32 v48, v44, v45
	s_waitcnt lgkmcnt(0)
	v_add_f32_dpp v38, v38, v38 row_mirror row_mask:0xf bank_mask:0xf bound_ctrl:1
	v_pk_fma_f32 v[90:91], v[118:119], v[38:39], v[40:41] op_sel_hi:[1,0,1]
	v_pk_fma_f32 v[88:89], v[120:121], v[38:39], v[42:43] op_sel_hi:[1,0,1]
	ds_read_b128 v[114:117], v92 offset:27136
	ds_read_b128 v[122:125], v92 offset:27648
	ds_read_b128 v[110:113], v92 offset:26880
	ds_read_b128 v[118:121], v92 offset:27392
	ds_read_b128 v[126:129], v92 offset:27904
	v_pk_mul_f32 v[36:37], v[90:91], v[28:29]
	v_pk_fma_f32 v[36:37], v[88:89], v[30:31], v[36:37]
	v_add_f32_e32 v38, v36, v37
	v_pk_mul_f32 v[40:41], v[102:103], v[130:131] op_sel_hi:[1,0]
	v_pk_mul_f32 v[42:43], v[104:105], v[130:131] op_sel_hi:[1,0]
	v_add_f32_dpp v38, v38, v38 quad_perm:[1,0,3,2] row_mask:0xf bank_mask:0xf bound_ctrl:1
	v_pk_fma_f32 v[40:41], v[90:91], v[24:25], v[40:41]
	v_pk_fma_f32 v[42:43], v[88:89], v[26:27], v[42:43]
	v_add_f32_dpp v38, v38, v38 quad_perm:[2,3,0,1] row_mask:0xf bank_mask:0xf bound_ctrl:1
	v_pk_mul_f32 v[44:45], v[90:91], v[54:55]
	v_pk_fma_f32 v[44:45], v[88:89], v[56:57], v[44:45]
	v_add_f32_dpp v38, v38, v38 row_half_mirror row_mask:0xf bank_mask:0xf bound_ctrl:1
	v_add_f32_e32 v49, v44, v45
	s_waitcnt lgkmcnt(0)
	v_add_f32_dpp v38, v38, v38 row_mirror row_mask:0xf bank_mask:0xf bound_ctrl:1
	v_pk_fma_f32 v[90:91], v[98:99], v[38:39], v[40:41] op_sel_hi:[1,0,1]
	v_pk_fma_f32 v[88:89], v[100:101], v[38:39], v[42:43] op_sel_hi:[1,0,1]
	ds_read_b128 v[28:31], v92 offset:28416
	ds_read_b128 v[102:105], v92 offset:28928
	ds_read_b128 v[24:27], v92 offset:28160
	ds_read_b128 v[98:101], v92 offset:28672
	ds_read_b128 v[50:53], v92 offset:29184
	ds_read2_b32 v[132:133], v136 offset0:96 offset1:112
	ds_write2st64_b32 v97, v48, v49 offset0:72 offset1:76
	v_pk_mul_f32 v[36:37], v[90:91], v[114:115]
	v_pk_fma_f32 v[36:37], v[88:89], v[116:117], v[36:37]
	v_add_f32_e32 v38, v36, v37
	v_pk_mul_f32 v[40:41], v[122:123], v[130:131] op_sel:[0,1] op_sel_hi:[1,1]
	v_pk_mul_f32 v[42:43], v[124:125], v[130:131] op_sel:[0,1] op_sel_hi:[1,1]
	v_add_f32_dpp v38, v38, v38 quad_perm:[1,0,3,2] row_mask:0xf bank_mask:0xf bound_ctrl:1
	v_pk_fma_f32 v[40:41], v[90:91], v[110:111], v[40:41]
	v_pk_fma_f32 v[42:43], v[88:89], v[112:113], v[42:43]
	v_add_f32_dpp v38, v38, v38 quad_perm:[2,3,0,1] row_mask:0xf bank_mask:0xf bound_ctrl:1
	v_pk_mul_f32 v[44:45], v[90:91], v[106:107]
	v_pk_fma_f32 v[44:45], v[88:89], v[108:109], v[44:45]
	v_add_f32_dpp v38, v38, v38 row_half_mirror row_mask:0xf bank_mask:0xf bound_ctrl:1
	v_add_f32_e32 v46, v44, v45
	s_waitcnt lgkmcnt(0)
	v_add_f32_dpp v38, v38, v38 row_mirror row_mask:0xf bank_mask:0xf bound_ctrl:1
	v_pk_fma_f32 v[90:91], v[118:119], v[38:39], v[40:41] op_sel_hi:[1,0,1]
	v_pk_fma_f32 v[88:89], v[120:121], v[38:39], v[42:43] op_sel_hi:[1,0,1]
	ds_read_b128 v[114:117], v92 offset:29696
	ds_read_b128 v[122:125], v92 offset:30208
	ds_read_b128 v[110:113], v92 offset:29440
	ds_read_b128 v[118:121], v92 offset:29952
	ds_read_b128 v[54:57], v92 offset:30464
	v_pk_mul_f32 v[36:37], v[90:91], v[28:29]
	v_pk_fma_f32 v[36:37], v[88:89], v[30:31], v[36:37]
	v_add_f32_e32 v38, v36, v37
	v_pk_mul_f32 v[40:41], v[102:103], v[132:133] op_sel_hi:[1,0]
	v_pk_mul_f32 v[42:43], v[104:105], v[132:133] op_sel_hi:[1,0]
	v_add_f32_dpp v38, v38, v38 quad_perm:[1,0,3,2] row_mask:0xf bank_mask:0xf bound_ctrl:1
	v_pk_fma_f32 v[40:41], v[90:91], v[24:25], v[40:41]
	v_pk_fma_f32 v[42:43], v[88:89], v[26:27], v[42:43]
	v_add_f32_dpp v38, v38, v38 quad_perm:[2,3,0,1] row_mask:0xf bank_mask:0xf bound_ctrl:1
	v_pk_mul_f32 v[44:45], v[90:91], v[126:127]
	v_pk_fma_f32 v[44:45], v[88:89], v[128:129], v[44:45]
	v_add_f32_dpp v38, v38, v38 row_half_mirror row_mask:0xf bank_mask:0xf bound_ctrl:1
	v_add_f32_e32 v47, v44, v45
	s_waitcnt lgkmcnt(0)
	v_add_f32_dpp v38, v38, v38 row_mirror row_mask:0xf bank_mask:0xf bound_ctrl:1
	v_pk_fma_f32 v[90:91], v[98:99], v[38:39], v[40:41] op_sel_hi:[1,0,1]
	v_pk_fma_f32 v[88:89], v[100:101], v[38:39], v[42:43] op_sel_hi:[1,0,1]
	ds_read_b128 v[28:31], v92 offset:30976
	ds_read_b128 v[102:105], v92 offset:31488
	ds_read_b128 v[24:27], v92 offset:30720
	ds_read_b128 v[98:101], v92 offset:31232
	ds_read_b128 v[106:109], v92 offset:31744
	ds_read2_b32 v[130:131], v136 offset0:128 offset1:144
	ds_write2st64_b32 v97, v46, v47 offset0:80 offset1:84
	v_pk_mul_f32 v[36:37], v[90:91], v[114:115]
	v_pk_fma_f32 v[36:37], v[88:89], v[116:117], v[36:37]
	v_add_f32_e32 v38, v36, v37
	v_pk_mul_f32 v[40:41], v[122:123], v[132:133] op_sel:[0,1] op_sel_hi:[1,1]
	v_pk_mul_f32 v[42:43], v[124:125], v[132:133] op_sel:[0,1] op_sel_hi:[1,1]
	v_add_f32_dpp v38, v38, v38 quad_perm:[1,0,3,2] row_mask:0xf bank_mask:0xf bound_ctrl:1
	v_pk_fma_f32 v[40:41], v[90:91], v[110:111], v[40:41]
	v_pk_fma_f32 v[42:43], v[88:89], v[112:113], v[42:43]
	v_add_f32_dpp v38, v38, v38 quad_perm:[2,3,0,1] row_mask:0xf bank_mask:0xf bound_ctrl:1
	v_pk_mul_f32 v[44:45], v[90:91], v[50:51]
	v_pk_fma_f32 v[44:45], v[88:89], v[52:53], v[44:45]
	v_add_f32_dpp v38, v38, v38 row_half_mirror row_mask:0xf bank_mask:0xf bound_ctrl:1
	v_add_f32_e32 v48, v44, v45
	s_waitcnt lgkmcnt(0)
	v_add_f32_dpp v38, v38, v38 row_mirror row_mask:0xf bank_mask:0xf bound_ctrl:1
	v_pk_fma_f32 v[90:91], v[118:119], v[38:39], v[40:41] op_sel_hi:[1,0,1]
	v_pk_fma_f32 v[88:89], v[120:121], v[38:39], v[42:43] op_sel_hi:[1,0,1]
	ds_read_b128 v[114:117], v92 offset:32256
	ds_read_b128 v[122:125], v92 offset:32768
	ds_read_b128 v[110:113], v92 offset:32000
	ds_read_b128 v[118:121], v92 offset:32512
	ds_read_b128 v[126:129], v92 offset:33024
	v_pk_mul_f32 v[36:37], v[90:91], v[28:29]
	v_pk_fma_f32 v[36:37], v[88:89], v[30:31], v[36:37]
	v_add_f32_e32 v38, v36, v37
	v_pk_mul_f32 v[40:41], v[102:103], v[130:131] op_sel_hi:[1,0]
	v_pk_mul_f32 v[42:43], v[104:105], v[130:131] op_sel_hi:[1,0]
	v_add_f32_dpp v38, v38, v38 quad_perm:[1,0,3,2] row_mask:0xf bank_mask:0xf bound_ctrl:1
	v_pk_fma_f32 v[40:41], v[90:91], v[24:25], v[40:41]
	v_pk_fma_f32 v[42:43], v[88:89], v[26:27], v[42:43]
	v_add_f32_dpp v38, v38, v38 quad_perm:[2,3,0,1] row_mask:0xf bank_mask:0xf bound_ctrl:1
	v_pk_mul_f32 v[44:45], v[90:91], v[54:55]
	v_pk_fma_f32 v[44:45], v[88:89], v[56:57], v[44:45]
	v_add_f32_dpp v38, v38, v38 row_half_mirror row_mask:0xf bank_mask:0xf bound_ctrl:1
	v_add_f32_e32 v49, v44, v45
	s_waitcnt lgkmcnt(0)
	v_add_f32_dpp v38, v38, v38 row_mirror row_mask:0xf bank_mask:0xf bound_ctrl:1
	v_pk_fma_f32 v[90:91], v[98:99], v[38:39], v[40:41] op_sel_hi:[1,0,1]
	v_pk_fma_f32 v[88:89], v[100:101], v[38:39], v[42:43] op_sel_hi:[1,0,1]
	ds_read_b128 v[28:31], v92 offset:33536
	ds_read_b128 v[102:105], v92 offset:34048
	ds_read_b128 v[24:27], v92 offset:33280
	ds_read_b128 v[98:101], v92 offset:33792
	ds_read_b128 v[50:53], v92 offset:34304
	ds_read2_b32 v[132:133], v136 offset0:160 offset1:176
	ds_write2st64_b32 v97, v48, v49 offset0:88 offset1:92
	v_pk_mul_f32 v[36:37], v[90:91], v[114:115]
	v_pk_fma_f32 v[36:37], v[88:89], v[116:117], v[36:37]
	v_add_f32_e32 v38, v36, v37
	v_pk_mul_f32 v[40:41], v[122:123], v[130:131] op_sel:[0,1] op_sel_hi:[1,1]
	v_pk_mul_f32 v[42:43], v[124:125], v[130:131] op_sel:[0,1] op_sel_hi:[1,1]
	v_add_f32_dpp v38, v38, v38 quad_perm:[1,0,3,2] row_mask:0xf bank_mask:0xf bound_ctrl:1
	v_pk_fma_f32 v[40:41], v[90:91], v[110:111], v[40:41]
	v_pk_fma_f32 v[42:43], v[88:89], v[112:113], v[42:43]
	v_add_f32_dpp v38, v38, v38 quad_perm:[2,3,0,1] row_mask:0xf bank_mask:0xf bound_ctrl:1
	v_pk_mul_f32 v[44:45], v[90:91], v[106:107]
	v_pk_fma_f32 v[44:45], v[88:89], v[108:109], v[44:45]
	v_add_f32_dpp v38, v38, v38 row_half_mirror row_mask:0xf bank_mask:0xf bound_ctrl:1
	v_add_f32_e32 v46, v44, v45
	s_waitcnt lgkmcnt(0)
	v_add_f32_dpp v38, v38, v38 row_mirror row_mask:0xf bank_mask:0xf bound_ctrl:1
	v_pk_fma_f32 v[90:91], v[118:119], v[38:39], v[40:41] op_sel_hi:[1,0,1]
	v_pk_fma_f32 v[88:89], v[120:121], v[38:39], v[42:43] op_sel_hi:[1,0,1]
	ds_read_b128 v[114:117], v92 offset:34816
	ds_read_b128 v[122:125], v92 offset:35328
	ds_read_b128 v[110:113], v92 offset:34560
	ds_read_b128 v[118:121], v92 offset:35072
	ds_read_b128 v[54:57], v92 offset:35584
	v_pk_mul_f32 v[36:37], v[90:91], v[28:29]
	v_pk_fma_f32 v[36:37], v[88:89], v[30:31], v[36:37]
	v_add_f32_e32 v38, v36, v37
	v_pk_mul_f32 v[40:41], v[102:103], v[132:133] op_sel_hi:[1,0]
	v_pk_mul_f32 v[42:43], v[104:105], v[132:133] op_sel_hi:[1,0]
	v_add_f32_dpp v38, v38, v38 quad_perm:[1,0,3,2] row_mask:0xf bank_mask:0xf bound_ctrl:1
	v_pk_fma_f32 v[40:41], v[90:91], v[24:25], v[40:41]
	v_pk_fma_f32 v[42:43], v[88:89], v[26:27], v[42:43]
	v_add_f32_dpp v38, v38, v38 quad_perm:[2,3,0,1] row_mask:0xf bank_mask:0xf bound_ctrl:1
	v_pk_mul_f32 v[44:45], v[90:91], v[126:127]
	v_pk_fma_f32 v[44:45], v[88:89], v[128:129], v[44:45]
	v_add_f32_dpp v38, v38, v38 row_half_mirror row_mask:0xf bank_mask:0xf bound_ctrl:1
	v_add_f32_e32 v47, v44, v45
	s_waitcnt lgkmcnt(0)
	v_add_f32_dpp v38, v38, v38 row_mirror row_mask:0xf bank_mask:0xf bound_ctrl:1
	v_pk_fma_f32 v[90:91], v[98:99], v[38:39], v[40:41] op_sel_hi:[1,0,1]
	v_pk_fma_f32 v[88:89], v[100:101], v[38:39], v[42:43] op_sel_hi:[1,0,1]
	ds_read_b128 v[28:31], v92 offset:36096
	ds_read_b128 v[102:105], v92 offset:36608
	ds_read_b128 v[24:27], v92 offset:35840
	ds_read_b128 v[98:101], v92 offset:36352
	ds_read_b128 v[106:109], v92 offset:36864
	ds_read2_b32 v[130:131], v136 offset0:192 offset1:208
	ds_write2st64_b32 v97, v46, v47 offset0:96 offset1:100
	v_pk_mul_f32 v[36:37], v[90:91], v[114:115]
	v_pk_fma_f32 v[36:37], v[88:89], v[116:117], v[36:37]
	v_add_f32_e32 v38, v36, v37
	v_pk_mul_f32 v[40:41], v[122:123], v[132:133] op_sel:[0,1] op_sel_hi:[1,1]
	v_pk_mul_f32 v[42:43], v[124:125], v[132:133] op_sel:[0,1] op_sel_hi:[1,1]
	v_add_f32_dpp v38, v38, v38 quad_perm:[1,0,3,2] row_mask:0xf bank_mask:0xf bound_ctrl:1
	v_pk_fma_f32 v[40:41], v[90:91], v[110:111], v[40:41]
	v_pk_fma_f32 v[42:43], v[88:89], v[112:113], v[42:43]
	v_add_f32_dpp v38, v38, v38 quad_perm:[2,3,0,1] row_mask:0xf bank_mask:0xf bound_ctrl:1
	v_pk_mul_f32 v[44:45], v[90:91], v[50:51]
	v_pk_fma_f32 v[44:45], v[88:89], v[52:53], v[44:45]
	v_add_f32_dpp v38, v38, v38 row_half_mirror row_mask:0xf bank_mask:0xf bound_ctrl:1
	v_add_f32_e32 v48, v44, v45
	s_waitcnt lgkmcnt(0)
	v_add_f32_dpp v38, v38, v38 row_mirror row_mask:0xf bank_mask:0xf bound_ctrl:1
	v_pk_fma_f32 v[90:91], v[118:119], v[38:39], v[40:41] op_sel_hi:[1,0,1]
	v_pk_fma_f32 v[88:89], v[120:121], v[38:39], v[42:43] op_sel_hi:[1,0,1]
	ds_read_b128 v[114:117], v92 offset:37376
	ds_read_b128 v[122:125], v92 offset:37888
	ds_read_b128 v[110:113], v92 offset:37120
	ds_read_b128 v[118:121], v92 offset:37632
	ds_read_b128 v[126:129], v92 offset:38144
	v_pk_mul_f32 v[36:37], v[90:91], v[28:29]
	v_pk_fma_f32 v[36:37], v[88:89], v[30:31], v[36:37]
	v_add_f32_e32 v38, v36, v37
	v_pk_mul_f32 v[40:41], v[102:103], v[130:131] op_sel_hi:[1,0]
	v_pk_mul_f32 v[42:43], v[104:105], v[130:131] op_sel_hi:[1,0]
	v_add_f32_dpp v38, v38, v38 quad_perm:[1,0,3,2] row_mask:0xf bank_mask:0xf bound_ctrl:1
	v_pk_fma_f32 v[40:41], v[90:91], v[24:25], v[40:41]
	v_pk_fma_f32 v[42:43], v[88:89], v[26:27], v[42:43]
	v_add_f32_dpp v38, v38, v38 quad_perm:[2,3,0,1] row_mask:0xf bank_mask:0xf bound_ctrl:1
	v_pk_mul_f32 v[44:45], v[90:91], v[54:55]
	v_pk_fma_f32 v[44:45], v[88:89], v[56:57], v[44:45]
	v_add_f32_dpp v38, v38, v38 row_half_mirror row_mask:0xf bank_mask:0xf bound_ctrl:1
	v_add_f32_e32 v49, v44, v45
	s_waitcnt lgkmcnt(0)
	v_add_f32_dpp v38, v38, v38 row_mirror row_mask:0xf bank_mask:0xf bound_ctrl:1
	v_pk_fma_f32 v[90:91], v[98:99], v[38:39], v[40:41] op_sel_hi:[1,0,1]
	v_pk_fma_f32 v[88:89], v[100:101], v[38:39], v[42:43] op_sel_hi:[1,0,1]
	ds_read_b128 v[28:31], v92 offset:38656
	ds_read_b128 v[102:105], v92 offset:39168
	ds_read_b128 v[24:27], v92 offset:38400
	ds_read_b128 v[98:101], v92 offset:38912
	ds_read_b128 v[50:53], v92 offset:39424
	ds_read2_b32 v[132:133], v136 offset0:224 offset1:240
	ds_write2st64_b32 v97, v48, v49 offset0:104 offset1:108
	v_pk_mul_f32 v[36:37], v[90:91], v[114:115]
	v_pk_fma_f32 v[36:37], v[88:89], v[116:117], v[36:37]
	v_add_f32_e32 v38, v36, v37
	v_pk_mul_f32 v[40:41], v[122:123], v[130:131] op_sel:[0,1] op_sel_hi:[1,1]
	v_pk_mul_f32 v[42:43], v[124:125], v[130:131] op_sel:[0,1] op_sel_hi:[1,1]
	v_add_f32_dpp v38, v38, v38 quad_perm:[1,0,3,2] row_mask:0xf bank_mask:0xf bound_ctrl:1
	v_pk_fma_f32 v[40:41], v[90:91], v[110:111], v[40:41]
	v_pk_fma_f32 v[42:43], v[88:89], v[112:113], v[42:43]
	v_add_f32_dpp v38, v38, v38 quad_perm:[2,3,0,1] row_mask:0xf bank_mask:0xf bound_ctrl:1
	v_pk_mul_f32 v[44:45], v[90:91], v[106:107]
	v_pk_fma_f32 v[44:45], v[88:89], v[108:109], v[44:45]
	v_add_f32_dpp v38, v38, v38 row_half_mirror row_mask:0xf bank_mask:0xf bound_ctrl:1
	v_add_f32_e32 v46, v44, v45
	s_waitcnt lgkmcnt(0)
	v_add_f32_dpp v38, v38, v38 row_mirror row_mask:0xf bank_mask:0xf bound_ctrl:1
	v_pk_fma_f32 v[90:91], v[118:119], v[38:39], v[40:41] op_sel_hi:[1,0,1]
	v_pk_fma_f32 v[88:89], v[120:121], v[38:39], v[42:43] op_sel_hi:[1,0,1]
	ds_read_b128 v[114:117], v92 offset:39936
	ds_read_b128 v[122:125], v92 offset:40448
	ds_read_b128 v[110:113], v92 offset:39680
	ds_read_b128 v[118:121], v92 offset:40192
	ds_read_b128 v[54:57], v92 offset:40704
	v_pk_mul_f32 v[36:37], v[90:91], v[28:29]
	v_pk_fma_f32 v[36:37], v[88:89], v[30:31], v[36:37]
	v_add_f32_e32 v38, v36, v37
	v_pk_mul_f32 v[40:41], v[102:103], v[132:133] op_sel_hi:[1,0]
	v_pk_mul_f32 v[42:43], v[104:105], v[132:133] op_sel_hi:[1,0]
	v_add_f32_dpp v38, v38, v38 quad_perm:[1,0,3,2] row_mask:0xf bank_mask:0xf bound_ctrl:1
	v_pk_fma_f32 v[40:41], v[90:91], v[24:25], v[40:41]
	v_pk_fma_f32 v[42:43], v[88:89], v[26:27], v[42:43]
	v_add_f32_dpp v38, v38, v38 quad_perm:[2,3,0,1] row_mask:0xf bank_mask:0xf bound_ctrl:1
	v_pk_mul_f32 v[44:45], v[90:91], v[126:127]
	v_pk_fma_f32 v[44:45], v[88:89], v[128:129], v[44:45]
	v_add_f32_dpp v38, v38, v38 row_half_mirror row_mask:0xf bank_mask:0xf bound_ctrl:1
	v_add_f32_e32 v47, v44, v45
	s_waitcnt lgkmcnt(0)
	v_add_f32_dpp v38, v38, v38 row_mirror row_mask:0xf bank_mask:0xf bound_ctrl:1
	v_pk_fma_f32 v[90:91], v[98:99], v[38:39], v[40:41] op_sel_hi:[1,0,1]
	v_pk_fma_f32 v[88:89], v[100:101], v[38:39], v[42:43] op_sel_hi:[1,0,1]
	ds_write2st64_b32 v97, v46, v47 offset0:112 offset1:116
	v_pk_mul_f32 v[36:37], v[90:91], v[114:115]
	v_pk_fma_f32 v[36:37], v[88:89], v[116:117], v[36:37]
	v_add_f32_e32 v38, v36, v37
	v_pk_mul_f32 v[40:41], v[122:123], v[132:133] op_sel:[0,1] op_sel_hi:[1,1]
	v_pk_mul_f32 v[42:43], v[124:125], v[132:133] op_sel:[0,1] op_sel_hi:[1,1]
	v_add_f32_dpp v38, v38, v38 quad_perm:[1,0,3,2] row_mask:0xf bank_mask:0xf bound_ctrl:1
	v_pk_fma_f32 v[40:41], v[90:91], v[110:111], v[40:41]
	v_pk_fma_f32 v[42:43], v[88:89], v[112:113], v[42:43]
	v_add_f32_dpp v38, v38, v38 quad_perm:[2,3,0,1] row_mask:0xf bank_mask:0xf bound_ctrl:1
	v_pk_mul_f32 v[44:45], v[90:91], v[50:51]
	v_pk_fma_f32 v[44:45], v[88:89], v[52:53], v[44:45]
	v_add_f32_dpp v38, v38, v38 row_half_mirror row_mask:0xf bank_mask:0xf bound_ctrl:1
	v_add_f32_e32 v48, v44, v45
	s_nop 0
	v_add_f32_dpp v38, v38, v38 row_mirror row_mask:0xf bank_mask:0xf bound_ctrl:1
	v_pk_fma_f32 v[90:91], v[118:119], v[38:39], v[40:41] op_sel_hi:[1,0,1]
	v_pk_fma_f32 v[88:89], v[120:121], v[38:39], v[42:43] op_sel_hi:[1,0,1]
	v_pk_mul_f32 v[44:45], v[90:91], v[54:55]
	v_pk_fma_f32 v[44:45], v[88:89], v[56:57], v[44:45]
	v_add_f32_e32 v49, v44, v45
	ds_write2st64_b32 v97, v48, v49 offset0:120 offset1:124
	s_branch .LBB0_640
